# attn loop single barrier per KV tile + all exps in PV gaps + generated tail
# speedup vs baseline: 1.0279x; 1.0279x over previous
; __device__ __forceinline__ int v_st(int k, int c) { const int kk = (k & ~0xC) | ((k & 4) << 1) | ((k & 8) >> 1); return ((kk >> 3) * 4 + (c >> 5)) * 512 + ((kk & 7) * 32 + (c & 31)) * 2; }
; __device__ __forceinline__ int v_rd_base(int lane) { return ((lane & 3) << 3) | (((lane >> 2) & 3) << 6) | (((lane >> 4) & 1) << 5) | (((lane >> 5) & 1) << 8); }
; #define SLOAD(i, k0) do { sr_[i].vs0 = LD8(&Vh[(long)((k0) + sr) * LDK + sc]); sr_[i].vs1 = LD8(&Vh[(long)((k0) + 32 + sr) * LDK + sc]); \
;     sr_[i].ks0 = LD8(&Kh[(long)((k0) + sr) * LDK + sc]); sr_[i].ks1 = LD8(&Kh[(long)((k0) + 32 + sr) * LDK + sc]); } while (0)
; #define SWRITE(b, i) do { *(bf16x8*)((char*)V_lds + (b) * SHM_V + vst0) = sr_[i].vs0;          \
;     *(bf16x8*)((char*)V_lds + (b) * SHM_V + vst1) = sr_[i].vs1; int kc = sc * 2;               \
;     *(bf16x8*)((char*)K_lds + (b) * SHM_K + KSWZ(sr, kc)) = sr_[i].ks0;                       \
;     *(bf16x8*)((char*)K_lds + (b) * SHM_K + KSWZ(32 + sr, kc)) = sr_[i].ks1; } while (0)
; #define SWAIT() asm volatile("s_waitcnt vmcnt(4)" ::: "memory")
; __device__ __forceinline__ void attn_body(const bf16_t* __restrict__ Qb, const bf16_t* __restrict__ Kh, const bf16_t* __restrict__ Vh, const bf16_t* __restrict__ Zb, ...
;     ...
;     float l_reg = 0; f32x16 o[4] = {}; bf16x8 qr[8];
;     const bf16_t* Qw = Qb + (long)(wid * QBLK + r32) * LDQ + hi * 8;
; #pragma unroll
;     for (int d0 = 0; d0 < 8; ++d0) qr[d0] = *reinterpret_cast<const bf16x8*>(Qw + d0 * 16);
;     const int sr = tid >> 4, sc = (tid & 15) * 8, vst0 = v_st(sr, sc), vst1 = v_st(32 + sr, sc);
;     const int vb0 = (int)(uintptr_t)V_lds + v_rd_base(lane);
;     ...
;     f32x16 pA0, pA1, pB0, pB1; bf16x8 pa0, pa1, pa2, pa3; const int NT = seq / KVBLK;
;     constexpr int SE = 0, SO = 1;
;     asm volatile("s_waitcnt vmcnt(0)" ::: "memory"); SWRITE(0, SE); __syncthreads();
;     qkt(pA0, pA1, K_lds, qr, r32, hi); partialSM(pA0, pA1, negBC);
;     SLOAD(SE, 2 * KVBLK);
;     SWAIT(); SWRITE(1, SO); __syncthreads();
;     if (__builtin_amdgcn_readfirstlane(tid) >= 256) __builtin_amdgcn_s_setprio(1);
;     for (int j = 1; j + 1 < NT; j += 2) {
.LBB0_489:
	v_and_b32_e32 v203, 63, v200
	v_exp_f32_e32 v235, v1
	v_lshlrev_b32_e32 v1, 4, v203
	v_exp_f32_e32 v233, v0
	v_exp_f32_e32 v231, v2
	v_lshlrev_b32_e32 v0, 3, v203
	v_and_b32_e32 v1, 0xc0, v1
	v_lshlrev_b32_e32 v2, 1, v203
	v_and_or_b32 v1, v0, 24, v1
	v_and_b32_e32 v2, 32, v2
	v_and_b32_e32 v0, 0x100, v0
	s_cmp_lg_u32 0, -1
	v_or3_b32 v0, v1, v2, v0
	s_cselect_b32 s42, 0, 0
	s_mov_b32 s23, s9
	v_add_u32_e32 v206, s42, v0
	s_addk_i32 s42, 0x4000
	v_add_u32_e32 v205, s42, v0
	v_lshl_add_u64 v[0:1], v[186:187], 0, s[22:23]
	v_exp_f32_e32 v234, v3
	v_exp_f32_e32 v230, v4
	v_exp_f32_e32 v232, v5
	v_exp_f32_e32 v228, v6
	v_exp_f32_e32 v229, v7
	v_exp_f32_e32 v225, v8
	v_exp_f32_e32 v227, v9
	v_exp_f32_e32 v224, v10
	v_exp_f32_e32 v226, v11
	v_exp_f32_e32 v221, v12
	v_exp_f32_e32 v223, v13
	v_exp_f32_e32 v181, v14
	v_exp_f32_e32 v222, v15
	v_mad_u64_u32 v[2:3], s[22:23], v0, s30, 0
	v_and_b32_e32 v0, 15, v200
	v_lshlrev_b32_e32 v0, 4, v0
	v_mad_i32_i24 v1, v1, s30, v3
	v_or3_b32 v0, v2, s41, v0
	v_mov_b32_e32 v204, 0
	s_mov_b32 s39, 4
	s_add_i32 s40, s33, -1
	v_lshl_add_u64 v[190:191], s[12:13], 0, v[0:1]
	v_mov_b32_e32 v0, 0
	v_mov_b32_e32 v1, v204
	v_mov_b32_e32 v2, v204
	v_mov_b32_e32 v3, v204
	v_mov_b32_e32 v4, v204
	v_mov_b32_e32 v5, v204
	v_mov_b32_e32 v6, v204
	v_mov_b32_e32 v7, v204
	v_mov_b32_e32 v8, v204
	v_mov_b32_e32 v9, v204
	v_mov_b32_e32 v10, v204
	v_mov_b32_e32 v11, v204
	v_mov_b32_e32 v12, v204
	v_mov_b32_e32 v13, v204
	v_mov_b32_e32 v14, v204
	v_mov_b32_e32 v15, v204
	v_mov_b32_e32 v16, 0
	v_mov_b32_e32 v17, v204
	v_mov_b32_e32 v18, v204
	v_mov_b32_e32 v19, v204
	v_mov_b32_e32 v20, v204
	v_mov_b32_e32 v21, v204
	v_mov_b32_e32 v22, v204
	v_mov_b32_e32 v23, v204
	v_mov_b32_e32 v24, v204
	v_mov_b32_e32 v25, v204
	v_mov_b32_e32 v26, v204
	v_mov_b32_e32 v27, v204
	v_mov_b32_e32 v28, v204
	v_mov_b32_e32 v29, v204
	v_mov_b32_e32 v30, v204
	v_mov_b32_e32 v31, v204
	v_mov_b32_e32 v32, 0
	v_mov_b32_e32 v33, v204
	v_mov_b32_e32 v34, v204
	v_mov_b32_e32 v35, v204
	v_mov_b32_e32 v36, v204
	v_mov_b32_e32 v37, v204
	v_mov_b32_e32 v38, v204
	v_mov_b32_e32 v39, v204
	v_mov_b32_e32 v40, v204
	v_mov_b32_e32 v41, v204
	v_mov_b32_e32 v42, v204
	v_mov_b32_e32 v43, v204
	v_mov_b32_e32 v44, v204
	v_mov_b32_e32 v45, v204
	v_mov_b32_e32 v46, v204
	v_mov_b32_e32 v47, v204
	v_mov_b32_e32 v48, 0
	v_mov_b32_e32 v49, v204
	v_mov_b32_e32 v50, v204
	v_mov_b32_e32 v51, v204
	v_mov_b32_e32 v52, v204
	v_mov_b32_e32 v53, v204
	v_mov_b32_e32 v54, v204
	v_mov_b32_e32 v55, v204
	v_mov_b32_e32 v56, v204
	v_mov_b32_e32 v57, v204
	v_mov_b32_e32 v58, v204
	v_mov_b32_e32 v59, v204
	v_mov_b32_e32 v60, v204
	v_mov_b32_e32 v61, v204
	v_mov_b32_e32 v62, v204
	v_mov_b32_e32 v63, v204
	v_exp_f32_e32 v64, v64
	v_exp_f32_e32 v65, v65
	v_exp_f32_e32 v66, v66
	v_exp_f32_e32 v67, v67
	v_exp_f32_e32 v68, v68
	v_exp_f32_e32 v69, v69
	v_exp_f32_e32 v70, v70
	v_exp_f32_e32 v71, v71
	v_exp_f32_e32 v72, v72
	v_exp_f32_e32 v73, v73
	v_exp_f32_e32 v74, v74
	v_exp_f32_e32 v75, v75
	v_exp_f32_e32 v76, v76
	v_exp_f32_e32 v77, v77
	v_exp_f32_e32 v78, v78
	v_exp_f32_e32 v79, v79
	s_mov_b32 s100, 0xfffa0000
	s_mov_b32 s101, -1
	s_mov_b32 s98, 0xfffd0000
	s_mov_b32 s99, -1
	v_add_u32_e32 v252, 0x10000, v207
	v_add_u32_e32 v253, 0x10000, v208
	v_lshl_add_u64 v[190:191], v[190:191], 0, s[100:101]
	s_mov_b32 s100, 0x60000
	s_mov_b32 s101, 0
.LBB0_490:
	ds_read_b128 v[236:239], v211 offset:49152
	ds_read_b128 v[240:243], v211 offset:57344
	ds_read_b128 v[244:247], v212 offset:49152
	ds_read_b128 v[248:251], v212 offset:57344
	v_add_f32_e32 v219, v233, v235
	v_cvt_pk_bf16_f32 v160, v233, v235
	v_add_f32_e32 v219, v231, v219
	s_waitcnt lgkmcnt(3)
	v_mfma_f32_32x32x16_bf16 v[96:111], v[236:239], v[116:119], 0
	v_cvt_pk_bf16_f32 v161, v231, v234
	v_add_f32_e32 v219, v234, v219
	v_cvt_pk_bf16_f32 v162, v230, v232
	v_add_f32_e32 v219, v230, v219
	v_cvt_pk_bf16_f32 v163, v228, v229
	s_waitcnt lgkmcnt(2)
	v_mfma_f32_32x32x16_bf16 v[80:95], v[240:243], v[116:119], 0
	ds_read_b128 v[236:239], v213 offset:49152
	ds_read_b128 v[240:243], v213 offset:57344
	v_add_f32_e32 v219, v232, v219
	v_cvt_pk_bf16_f32 v164, v225, v227
	v_add_f32_e32 v219, v228, v219
	v_cvt_pk_bf16_f32 v165, v224, v226
	v_add_f32_e32 v219, v229, v219
	s_waitcnt lgkmcnt(3)
	v_mfma_f32_32x32x16_bf16 v[96:111], v[244:247], v[124:127], v[96:111]
	v_cvt_pk_bf16_f32 v166, v221, v223
	v_add_f32_e32 v219, v225, v219
	v_cvt_pk_bf16_f32 v167, v181, v222
	v_add_f32_e32 v219, v227, v219
	s_waitcnt lgkmcnt(2)
	v_mfma_f32_32x32x16_bf16 v[80:95], v[248:251], v[124:127], v[80:95]
	ds_read_b128 v[244:247], v214 offset:49152
	ds_read_b128 v[248:251], v214 offset:57344
	v_cvt_pk_bf16_f32 v168, v64, v65
	v_add_f32_e32 v219, v224, v219
	v_cvt_pk_bf16_f32 v169, v66, v67
	v_add_f32_e32 v219, v226, v219
	s_waitcnt lgkmcnt(3)
	v_mfma_f32_32x32x16_bf16 v[96:111], v[236:239], v[112:115], v[96:111]
	v_cvt_pk_bf16_f32 v170, v68, v69
	v_add_f32_e32 v219, v221, v219
	v_cvt_pk_bf16_f32 v171, v70, v71
	v_add_f32_e32 v219, v223, v219
	s_waitcnt lgkmcnt(2)
	v_mfma_f32_32x32x16_bf16 v[80:95], v[240:243], v[112:115], v[80:95]
	ds_read_b128 v[236:239], v215 offset:49152
	ds_read_b128 v[240:243], v215 offset:57344
	v_cvt_pk_bf16_f32 v172, v72, v73
	v_add_f32_e32 v219, v181, v219
	v_cvt_pk_bf16_f32 v173, v74, v75
	v_add_f32_e32 v219, v222, v219
	s_waitcnt lgkmcnt(3)
	v_mfma_f32_32x32x16_bf16 v[96:111], v[244:247], v[120:123], v[96:111]
	v_cvt_pk_bf16_f32 v174, v76, v77
	v_add_f32_e32 v219, v64, v219
	v_cvt_pk_bf16_f32 v175, v78, v79
	v_add_f32_e32 v219, v65, v219
	s_waitcnt lgkmcnt(2)
; #define SBAR() __builtin_amdgcn_sched_barrier(0)
; #define SLOAD(i, k0) do { sr_[i].vs0 = LD8(&Vh[(long)((k0) + sr) * LDK + sc]); sr_[i].vs1 = LD8(&Vh[(long)((k0) + 32 + sr) * LDK + sc]); \
;     sr_[i].ks0 = LD8(&Kh[(long)((k0) + sr) * LDK + sc]); sr_[i].ks1 = LD8(&Kh[(long)((k0) + 32 + sr) * LDK + sc]); } while (0)
; #define SWRITE(b, i) do { *(bf16x8*)((char*)V_lds + (b) * SHM_V + vst0) = sr_[i].vs0;          \
;     *(bf16x8*)((char*)V_lds + (b) * SHM_V + vst1) = sr_[i].vs1; int kc = sc * 2;               \
;     *(bf16x8*)((char*)K_lds + (b) * SHM_K + KSWZ(sr, kc)) = sr_[i].ks0;                       \
;     *(bf16x8*)((char*)K_lds + (b) * SHM_K + KSWZ(32 + sr, kc)) = sr_[i].ks1; } while (0)
; #define SWAIT() asm volatile("s_waitcnt vmcnt(4)" ::: "memory")
; __device__ __forceinline__ void finishSM(f32x16& p0, f32x16& p1, float alpha, float& l_reg, bf16x8& pa0, bf16x8& pa1, bf16x8& pa2, bf16x8& pa3) {
;     for (int r = 0; r < 16; ++r) p1[r] = __builtin_amdgcn_exp2f(p1[r]);
;     float ps = 0; for (int r = 0; r < 16; ++r) ps += p0[r]; for (int r = 0; r < 16; ++r) ps += p1[r];
;     { auto rr = __builtin_amdgcn_permlane32_swap(__float_as_uint(ps), __float_as_uint(ps), false, false);
;       ps = __uint_as_float(rr[0]) + __uint_as_float(rr[1]); }
;     l_reg = l_reg * alpha + ps;
;     ...
;     PK4(p0, 0, pa0); PK4(p0, 8, pa1); PK4(p1, 0, pa2); PK4(p1, 8, pa3);
;     ...
; }
; __device__ __forceinline__ void attn_body(const bf16_t* __restrict__ Qb, const bf16_t* __restrict__ Kh, const bf16_t* __restrict__ Vh, const bf16_t* __restrict__ Zb, ...
;     ...
;     for (int j = 1; j + 1 < NT; j += 2) {
;         SBAR(); qkt(pB0, pB1, (bf16_t*)((char*)K_lds + SHM_K), qr, r32, hi);
;         finishSM(pA0, pA1, 1.f, l_reg, pa0, pa1, pa2, pa3); SBAR();
;         SLOAD(SO, (j + 2) * KVBLK); SBAR();
;         pv_d0(o, vb0, pa0, pa1, pa2, pa3); partialSM(pB0, pB1, negBC);
;         __syncthreads(); SWAIT(); SWRITE(0, SE);
	v_mfma_f32_32x32x16_bf16 v[80:95], v[248:251], v[120:123], v[80:95]
	ds_read_b128 v[244:247], v216 offset:49152
	ds_read_b128 v[248:251], v216 offset:57344
	v_permlane32_swap_b32_e32 v160, v162
	v_add_f32_e32 v219, v66, v219
	s_waitcnt lgkmcnt(3)
	v_mfma_f32_32x32x16_bf16 v[96:111], v[236:239], v[132:135], v[96:111]
	v_permlane32_swap_b32_e32 v161, v163
	v_add_f32_e32 v219, v67, v219
	v_permlane32_swap_b32_e32 v164, v166
	s_waitcnt lgkmcnt(2)
	v_mfma_f32_32x32x16_bf16 v[80:95], v[240:243], v[132:135], v[80:95]
	ds_read_b128 v[236:239], v217 offset:49152
	ds_read_b128 v[240:243], v217 offset:57344
	v_add_f32_e32 v219, v68, v219
	v_permlane32_swap_b32_e32 v165, v167
	v_add_f32_e32 v219, v69, v219
	s_waitcnt lgkmcnt(3)
	v_mfma_f32_32x32x16_bf16 v[96:111], v[244:247], v[140:143], v[96:111]
	v_permlane32_swap_b32_e32 v168, v170
	v_add_f32_e32 v219, v70, v219
	s_waitcnt lgkmcnt(2)
	v_mfma_f32_32x32x16_bf16 v[80:95], v[248:251], v[140:143], v[80:95]
	ds_read_b128 v[244:247], v218 offset:49152
	ds_read_b128 v[248:251], v218 offset:57344
	v_permlane32_swap_b32_e32 v169, v171
	v_add_f32_e32 v219, v71, v219
	v_permlane32_swap_b32_e32 v172, v174
	s_waitcnt lgkmcnt(3)
	v_mfma_f32_32x32x16_bf16 v[96:111], v[236:239], v[128:131], v[96:111]
	v_add_f32_e32 v219, v72, v219
	v_permlane32_swap_b32_e32 v173, v175
	v_add_f32_e32 v219, v73, v219
	s_waitcnt lgkmcnt(2)
	v_mfma_f32_32x32x16_bf16 v[80:95], v[240:243], v[128:131], v[80:95]
	ds_read_b64_tr_b16 v[236:237], v206 offset:0
	ds_read_b64_tr_b16 v[238:239], v206 offset:2048
	ds_read_b64_tr_b16 v[240:241], v206 offset:4096
	ds_read_b64_tr_b16 v[242:243], v206 offset:6144
	v_add_f32_e32 v219, v74, v219
	v_add_f32_e32 v219, v75, v219
	v_add_f32_e32 v219, v76, v219
	v_add_f32_e32 v219, v77, v219
	s_waitcnt lgkmcnt(5)
	v_mfma_f32_32x32x16_bf16 v[96:111], v[244:247], v[136:139], v[96:111]
	v_add_f32_e32 v219, v78, v219
	v_add_f32_e32 v219, v79, v219
	v_mov_b32_e32 v220, v219
	s_nop 1
	s_waitcnt lgkmcnt(4)
	v_mfma_f32_32x32x16_bf16 v[80:95], v[248:251], v[136:139], v[80:95]
	v_permlane32_swap_b32_e32 v219, v220
	v_add_f32_e32 v219, v219, v220
	v_add_f32_e32 v204, v204, v219
	ds_read_b64_tr_b16 v[244:245], v206 offset:8192
	ds_read_b64_tr_b16 v[246:247], v206 offset:10240
	ds_read_b64_tr_b16 v[248:249], v206 offset:12288
	ds_read_b64_tr_b16 v[250:251], v206 offset:14336
	s_and_b64 vcc, exec, s[6:7]
	s_cbranch_vccnz .Lat2_noshift_A
	s_nop 15
	v_pk_add_f32 v[110:111], v[182:183], v[110:111]
	v_pk_add_f32 v[108:109], v[182:183], v[108:109]
	v_pk_add_f32 v[106:107], v[182:183], v[106:107]
	v_pk_add_f32 v[104:105], v[182:183], v[104:105]
	v_pk_add_f32 v[102:103], v[182:183], v[102:103]
	v_pk_add_f32 v[100:101], v[182:183], v[100:101]
	v_pk_add_f32 v[98:99], v[182:183], v[98:99]
	v_pk_add_f32 v[96:97], v[182:183], v[96:97]
	v_pk_add_f32 v[94:95], v[182:183], v[94:95]
	v_pk_add_f32 v[92:93], v[182:183], v[92:93]
	v_pk_add_f32 v[90:91], v[182:183], v[90:91]
	v_pk_add_f32 v[88:89], v[182:183], v[88:89]
	v_pk_add_f32 v[86:87], v[182:183], v[86:87]
	v_pk_add_f32 v[84:85], v[182:183], v[84:85]
	v_pk_add_f32 v[82:83], v[182:183], v[82:83]
	v_pk_add_f32 v[80:81], v[182:183], v[80:81]
.Lat2_noshift_A:
	s_waitcnt lgkmcnt(6)
	v_mfma_f32_32x32x16_bf16 v[0:15], v[160:163], v[236:239], v[0:15]
	ds_read_b64_tr_b16 v[236:237], v206 offset:512
	ds_read_b64_tr_b16 v[238:239], v206 offset:2560
	s_waitcnt lgkmcnt(6)
	v_mfma_f32_32x32x16_bf16 v[0:15], v[164:167], v[240:243], v[0:15]
	ds_read_b64_tr_b16 v[240:241], v206 offset:4608
	ds_read_b64_tr_b16 v[242:243], v206 offset:6656
	s_waitcnt vmcnt(0)
	ds_write_b128 v209, v[148:151] offset:32768
	v_exp_f32_e32 v181, v96
	v_exp_f32_e32 v221, v97
	s_waitcnt lgkmcnt(7)
	v_mfma_f32_32x32x16_bf16 v[0:15], v[168:171], v[244:247], v[0:15]
	ds_read_b64_tr_b16 v[244:245], v206 offset:8704
	ds_read_b64_tr_b16 v[246:247], v206 offset:10752
	ds_write_b128 v210, v[152:155] offset:32768
	v_exp_f32_e32 v222, v98
	v_exp_f32_e32 v223, v99
	s_waitcnt lgkmcnt(8)
	v_mfma_f32_32x32x16_bf16 v[0:15], v[172:175], v[248:251], v[0:15]
	ds_read_b64_tr_b16 v[248:249], v206 offset:12800
	ds_read_b64_tr_b16 v[250:251], v206 offset:14848
	ds_write_b128 v252, v[144:147] offset:16384
	v_exp_f32_e32 v224, v100
	v_exp_f32_e32 v225, v101
	s_waitcnt lgkmcnt(9)
	v_mfma_f32_32x32x16_bf16 v[16:31], v[160:163], v[236:239], v[16:31]
	ds_read_b64_tr_b16 v[236:237], v206 offset:1024
	ds_read_b64_tr_b16 v[238:239], v206 offset:3072
	ds_write_b128 v253, v[156:159] offset:16384
	v_exp_f32_e32 v226, v102
	v_exp_f32_e32 v227, v103
	s_waitcnt lgkmcnt(10)
	v_mfma_f32_32x32x16_bf16 v[16:31], v[164:167], v[240:243], v[16:31]
	ds_read_b64_tr_b16 v[240:241], v206 offset:5120
	ds_read_b64_tr_b16 v[242:243], v206 offset:7168
	v_exp_f32_e32 v228, v104
	v_exp_f32_e32 v229, v105
	s_waitcnt lgkmcnt(9)
	v_mfma_f32_32x32x16_bf16 v[16:31], v[168:171], v[244:247], v[16:31]
	ds_read_b64_tr_b16 v[244:245], v206 offset:9216
	ds_read_b64_tr_b16 v[246:247], v206 offset:11264
	v_lshl_add_u64 v[144:145], v[190:191], 0, s[98:99]
	global_load_dwordx4 v[156:159], v[190:191], off
	global_load_dwordx4 v[144:147], v[144:145], off
	v_exp_f32_e32 v230, v106
	v_exp_f32_e32 v231, v107
	s_waitcnt lgkmcnt(8)
	v_mfma_f32_32x32x16_bf16 v[16:31], v[172:175], v[248:251], v[16:31]
	ds_read_b64_tr_b16 v[248:249], v206 offset:13312
	ds_read_b64_tr_b16 v[250:251], v206 offset:15360
	v_exp_f32_e32 v232, v108
	v_exp_f32_e32 v233, v109
	s_waitcnt lgkmcnt(7)
; #define SBAR() __builtin_amdgcn_sched_barrier(0)
; #define SWRITE(b, i) do { *(bf16x8*)((char*)V_lds + (b) * SHM_V + vst0) = sr_[i].vs0;          \
;     *(bf16x8*)((char*)V_lds + (b) * SHM_V + vst1) = sr_[i].vs1; int kc = sc * 2;               \
;     *(bf16x8*)((char*)K_lds + (b) * SHM_K + KSWZ(sr, kc)) = sr_[i].ks0;                       \
;     *(bf16x8*)((char*)K_lds + (b) * SHM_K + KSWZ(32 + sr, kc)) = sr_[i].ks1; } while (0)
; #define SWAIT() asm volatile("s_waitcnt vmcnt(4)" ::: "memory")
; template <int D0> __device__ __forceinline__ void pv_one(f32x16& od, int vb, bf16x8 pa0, bf16x8 pa1, bf16x8 pa2, bf16x8 pa3) {
;     const s16x4 l0 = tr_read<v_rd_off(D0, 0, 0)>(vb), h0 = tr_read<v_rd_off(D0, 0, 1)>(vb), l1 = tr_read<v_rd_off(D0, 1, 0)>(vb), h1 = tr_read<v_rd_off(D0, 1, 1)>(vb);
;     const s16x4 l2 = tr_read<v_rd_off(D0, 2, 0)>(vb), h2 = tr_read<v_rd_off(D0, 2, 1)>(vb), l3 = tr_read<v_rd_off(D0, 3, 0)>(vb), h3 = tr_read<v_rd_off(D0, 3, 1)>(vb);
;     asm volatile("s_waitcnt lgkmcnt(0)" ::: "memory"); SBAR();
;     ...
;     od = __builtin_amdgcn_mfma_f32_32x32x16_bf16(pa0, PK(l0, h0), od, 0, 0, 0);
;     od = __builtin_amdgcn_mfma_f32_32x32x16_bf16(pa1, PK(l1, h1), od, 0, 0, 0);
;     od = __builtin_amdgcn_mfma_f32_32x32x16_bf16(pa2, PK(l2, h2), od, 0, 0, 0);
;     od = __builtin_amdgcn_mfma_f32_32x32x16_bf16(pa3, PK(l3, h3), od, 0, 0, 0);
;     ...
; }
; __device__ __forceinline__ void pv_d0(f32x16* o, int vb, bf16x8 pa0, bf16x8 pa1, bf16x8 pa2, bf16x8 pa3) {
;     pv_one<0>(o[0], vb, pa0, pa1, pa2, pa3); pv_one<1>(o[1], vb, pa0, pa1, pa2, pa3); pv_one<2>(o[2], vb, pa0, pa1, pa2, pa3); pv_one<3>(o[3], vb, pa0, pa1, pa2, pa3);
; __device__ __forceinline__ void attn_body(const bf16_t* __restrict__ Qb, const bf16_t* __restrict__ Kh, const bf16_t* __restrict__ Vh, const bf16_t* __restrict__ Zb, ...
;     ...
;         pv_d0(o, vb0, pa0, pa1, pa2, pa3); partialSM(pB0, pB1, negBC);
;         __syncthreads(); SWAIT(); SWRITE(0, SE);
;         __syncthreads();
;         SBAR(); qkt(pA0, pA1, K_lds, qr, r32, hi);
;         finishSM(pB0, pB1, 1.f, l_reg, pa0, pa1, pa2, pa3); SBAR();
	v_mfma_f32_32x32x16_bf16 v[32:47], v[160:163], v[236:239], v[32:47]
	ds_read_b64_tr_b16 v[236:237], v206 offset:1536
	ds_read_b64_tr_b16 v[238:239], v206 offset:3584
	v_lshl_add_u64 v[190:191], v[190:191], 0, s[100:101]
	v_lshl_add_u64 v[148:149], v[190:191], 0, s[98:99]
	global_load_dwordx4 v[152:155], v[190:191], off offset:-512
	global_load_dwordx4 v[148:151], v[148:149], off offset:-512
	v_exp_f32_e32 v234, v110
	v_exp_f32_e32 v235, v111
	s_waitcnt lgkmcnt(6)
	v_mfma_f32_32x32x16_bf16 v[32:47], v[164:167], v[240:243], v[32:47]
	ds_read_b64_tr_b16 v[240:241], v206 offset:5632
	ds_read_b64_tr_b16 v[242:243], v206 offset:7680
	v_exp_f32_e32 v80, v80
	v_exp_f32_e32 v81, v81
	s_waitcnt lgkmcnt(6)
	v_mfma_f32_32x32x16_bf16 v[32:47], v[168:171], v[244:247], v[32:47]
	ds_read_b64_tr_b16 v[244:245], v206 offset:9728
	ds_read_b64_tr_b16 v[246:247], v206 offset:11776
	v_exp_f32_e32 v82, v82
	v_exp_f32_e32 v83, v83
	s_waitcnt lgkmcnt(6)
	v_mfma_f32_32x32x16_bf16 v[32:47], v[172:175], v[248:251], v[32:47]
	ds_read_b64_tr_b16 v[248:249], v206 offset:13824
	ds_read_b64_tr_b16 v[250:251], v206 offset:15872
	v_exp_f32_e32 v84, v84
	v_exp_f32_e32 v85, v85
	s_waitcnt lgkmcnt(6)
	v_mfma_f32_32x32x16_bf16 v[48:63], v[160:163], v[236:239], v[48:63]
	v_exp_f32_e32 v86, v86
	v_exp_f32_e32 v87, v87
	s_waitcnt lgkmcnt(4)
	v_mfma_f32_32x32x16_bf16 v[48:63], v[164:167], v[240:243], v[48:63]
	v_exp_f32_e32 v88, v88
	v_exp_f32_e32 v89, v89
	v_exp_f32_e32 v90, v90
	s_waitcnt lgkmcnt(2)
	v_mfma_f32_32x32x16_bf16 v[48:63], v[168:171], v[244:247], v[48:63]
	v_exp_f32_e32 v91, v91
	v_exp_f32_e32 v92, v92
	v_exp_f32_e32 v93, v93
	s_waitcnt lgkmcnt(0)
	v_mfma_f32_32x32x16_bf16 v[48:63], v[172:175], v[248:251], v[48:63]
	v_exp_f32_e32 v94, v94
	v_exp_f32_e32 v95, v95
	v_mov_b32_e32 v252, v207
	v_mov_b32_e32 v253, v208
	s_waitcnt lgkmcnt(0)
	s_barrier
	ds_read_b128 v[236:239], v211 offset:32768
	ds_read_b128 v[240:243], v211 offset:40960
	ds_read_b128 v[244:247], v212 offset:32768
	ds_read_b128 v[248:251], v212 offset:40960
	v_add_f32_e32 v219, v181, v221
	v_cvt_pk_bf16_f32 v160, v181, v221
	v_add_f32_e32 v219, v222, v219
	s_waitcnt lgkmcnt(3)
	v_mfma_f32_32x32x16_bf16 v[96:111], v[236:239], v[116:119], 0
	v_cvt_pk_bf16_f32 v161, v222, v223
	v_add_f32_e32 v219, v223, v219
	v_cvt_pk_bf16_f32 v162, v224, v225
	v_add_f32_e32 v219, v224, v219
	v_cvt_pk_bf16_f32 v163, v226, v227
	s_waitcnt lgkmcnt(2)
	v_mfma_f32_32x32x16_bf16 v[64:79], v[240:243], v[116:119], 0
	ds_read_b128 v[236:239], v213 offset:32768
	ds_read_b128 v[240:243], v213 offset:40960
	v_add_f32_e32 v219, v225, v219
	v_cvt_pk_bf16_f32 v164, v228, v229
	v_add_f32_e32 v219, v226, v219
	v_cvt_pk_bf16_f32 v165, v230, v231
	v_add_f32_e32 v219, v227, v219
	s_waitcnt lgkmcnt(3)
	v_mfma_f32_32x32x16_bf16 v[96:111], v[244:247], v[124:127], v[96:111]
	v_cvt_pk_bf16_f32 v166, v232, v233
	v_add_f32_e32 v219, v228, v219
	v_cvt_pk_bf16_f32 v167, v234, v235
	v_add_f32_e32 v219, v229, v219
	s_waitcnt lgkmcnt(2)
	v_mfma_f32_32x32x16_bf16 v[64:79], v[248:251], v[124:127], v[64:79]
	ds_read_b128 v[244:247], v214 offset:32768
	ds_read_b128 v[248:251], v214 offset:40960
	v_cvt_pk_bf16_f32 v168, v80, v81
	v_add_f32_e32 v219, v230, v219
	v_cvt_pk_bf16_f32 v169, v82, v83
	v_add_f32_e32 v219, v231, v219
	s_waitcnt lgkmcnt(3)
	v_mfma_f32_32x32x16_bf16 v[96:111], v[236:239], v[112:115], v[96:111]
	v_cvt_pk_bf16_f32 v170, v84, v85
	v_add_f32_e32 v219, v232, v219
	v_cvt_pk_bf16_f32 v171, v86, v87
	v_add_f32_e32 v219, v233, v219
	s_waitcnt lgkmcnt(2)
	v_mfma_f32_32x32x16_bf16 v[64:79], v[240:243], v[112:115], v[64:79]
	ds_read_b128 v[236:239], v215 offset:32768
	ds_read_b128 v[240:243], v215 offset:40960
	v_cvt_pk_bf16_f32 v172, v88, v89
	v_add_f32_e32 v219, v234, v219
	v_cvt_pk_bf16_f32 v173, v90, v91
	v_add_f32_e32 v219, v235, v219
	s_waitcnt lgkmcnt(3)
	v_mfma_f32_32x32x16_bf16 v[96:111], v[244:247], v[120:123], v[96:111]
	v_cvt_pk_bf16_f32 v174, v92, v93
	v_add_f32_e32 v219, v80, v219
	v_cvt_pk_bf16_f32 v175, v94, v95
	v_add_f32_e32 v219, v81, v219
	s_waitcnt lgkmcnt(2)
	v_mfma_f32_32x32x16_bf16 v[64:79], v[248:251], v[120:123], v[64:79]
	ds_read_b128 v[244:247], v216 offset:32768
	ds_read_b128 v[248:251], v216 offset:40960
	v_permlane32_swap_b32_e32 v160, v162
	v_add_f32_e32 v219, v82, v219
	s_waitcnt lgkmcnt(3)
	v_mfma_f32_32x32x16_bf16 v[96:111], v[236:239], v[132:135], v[96:111]
	v_permlane32_swap_b32_e32 v161, v163
	v_add_f32_e32 v219, v83, v219
	v_permlane32_swap_b32_e32 v164, v166
	s_waitcnt lgkmcnt(2)
	v_mfma_f32_32x32x16_bf16 v[64:79], v[240:243], v[132:135], v[64:79]
	ds_read_b128 v[236:239], v217 offset:32768
	ds_read_b128 v[240:243], v217 offset:40960
	v_add_f32_e32 v219, v84, v219
	v_permlane32_swap_b32_e32 v165, v167
	v_add_f32_e32 v219, v85, v219
	s_waitcnt lgkmcnt(3)
	v_mfma_f32_32x32x16_bf16 v[96:111], v[244:247], v[140:143], v[96:111]
	v_permlane32_swap_b32_e32 v168, v170
	v_add_f32_e32 v219, v86, v219
	s_waitcnt lgkmcnt(2)
	v_mfma_f32_32x32x16_bf16 v[64:79], v[248:251], v[140:143], v[64:79]
	ds_read_b128 v[244:247], v218 offset:32768
	ds_read_b128 v[248:251], v218 offset:40960
	v_permlane32_swap_b32_e32 v169, v171
	v_add_f32_e32 v219, v87, v219
	v_permlane32_swap_b32_e32 v172, v174
	s_waitcnt lgkmcnt(3)
	v_mfma_f32_32x32x16_bf16 v[96:111], v[236:239], v[128:131], v[96:111]
	v_add_f32_e32 v219, v88, v219
	v_permlane32_swap_b32_e32 v173, v175
	v_add_f32_e32 v219, v89, v219
	s_waitcnt lgkmcnt(2)
	v_mfma_f32_32x32x16_bf16 v[64:79], v[240:243], v[128:131], v[64:79]
	ds_read_b64_tr_b16 v[236:237], v205 offset:0
	ds_read_b64_tr_b16 v[238:239], v205 offset:2048
	ds_read_b64_tr_b16 v[240:241], v205 offset:4096
	ds_read_b64_tr_b16 v[242:243], v205 offset:6144
	v_add_f32_e32 v219, v90, v219
	v_add_f32_e32 v219, v91, v219
	v_add_f32_e32 v219, v92, v219
	v_add_f32_e32 v219, v93, v219
	s_waitcnt lgkmcnt(5)
	v_mfma_f32_32x32x16_bf16 v[96:111], v[244:247], v[136:139], v[96:111]
	v_add_f32_e32 v219, v94, v219
	v_add_f32_e32 v219, v95, v219
	v_mov_b32_e32 v220, v219
	s_nop 1
	s_waitcnt lgkmcnt(4)
	v_mfma_f32_32x32x16_bf16 v[64:79], v[248:251], v[136:139], v[64:79]
	v_permlane32_swap_b32_e32 v219, v220
	v_add_f32_e32 v219, v219, v220
	v_add_f32_e32 v204, v204, v219
	ds_read_b64_tr_b16 v[244:245], v205 offset:8192
	ds_read_b64_tr_b16 v[246:247], v205 offset:10240
	ds_read_b64_tr_b16 v[248:249], v205 offset:12288
	ds_read_b64_tr_b16 v[250:251], v205 offset:14336
	s_and_b64 vcc, exec, s[6:7]
	s_cbranch_vccnz .Lat2_noshift_B
; #define SBAR() __builtin_amdgcn_sched_barrier(0)
; #define SLOAD(i, k0) do { sr_[i].vs0 = LD8(&Vh[(long)((k0) + sr) * LDK + sc]); sr_[i].vs1 = LD8(&Vh[(long)((k0) + 32 + sr) * LDK + sc]); \
;     sr_[i].ks0 = LD8(&Kh[(long)((k0) + sr) * LDK + sc]); sr_[i].ks1 = LD8(&Kh[(long)((k0) + 32 + sr) * LDK + sc]); } while (0)
; #define SWRITE(b, i) do { *(bf16x8*)((char*)V_lds + (b) * SHM_V + vst0) = sr_[i].vs0;          \
;     *(bf16x8*)((char*)V_lds + (b) * SHM_V + vst1) = sr_[i].vs1; int kc = sc * 2;               \
;     *(bf16x8*)((char*)K_lds + (b) * SHM_K + KSWZ(sr, kc)) = sr_[i].ks0;                       \
;     *(bf16x8*)((char*)K_lds + (b) * SHM_K + KSWZ(32 + sr, kc)) = sr_[i].ks1; } while (0)
; #define SWAIT() asm volatile("s_waitcnt vmcnt(4)" ::: "memory")
; template <int D0> __device__ __forceinline__ void pv_one(f32x16& od, int vb, bf16x8 pa0, bf16x8 pa1, bf16x8 pa2, bf16x8 pa3) {
;     const s16x4 l0 = tr_read<v_rd_off(D0, 0, 0)>(vb), h0 = tr_read<v_rd_off(D0, 0, 1)>(vb), l1 = tr_read<v_rd_off(D0, 1, 0)>(vb), h1 = tr_read<v_rd_off(D0, 1, 1)>(vb);
;     const s16x4 l2 = tr_read<v_rd_off(D0, 2, 0)>(vb), h2 = tr_read<v_rd_off(D0, 2, 1)>(vb), l3 = tr_read<v_rd_off(D0, 3, 0)>(vb), h3 = tr_read<v_rd_off(D0, 3, 1)>(vb);
;     asm volatile("s_waitcnt lgkmcnt(0)" ::: "memory"); SBAR();
;     ...
;     od = __builtin_amdgcn_mfma_f32_32x32x16_bf16(pa0, PK(l0, h0), od, 0, 0, 0);
;     od = __builtin_amdgcn_mfma_f32_32x32x16_bf16(pa1, PK(l1, h1), od, 0, 0, 0);
;     od = __builtin_amdgcn_mfma_f32_32x32x16_bf16(pa2, PK(l2, h2), od, 0, 0, 0);
;     od = __builtin_amdgcn_mfma_f32_32x32x16_bf16(pa3, PK(l3, h3), od, 0, 0, 0);
;     ...
; }
; __device__ __forceinline__ void pv_d0(f32x16* o, int vb, bf16x8 pa0, bf16x8 pa1, bf16x8 pa2, bf16x8 pa3) {
;     pv_one<0>(o[0], vb, pa0, pa1, pa2, pa3); pv_one<1>(o[1], vb, pa0, pa1, pa2, pa3); pv_one<2>(o[2], vb, pa0, pa1, pa2, pa3); pv_one<3>(o[3], vb, pa0, pa1, pa2, pa3);
; __device__ __forceinline__ void attn_body(const bf16_t* __restrict__ Qb, const bf16_t* __restrict__ Kh, const bf16_t* __restrict__ Vh, const bf16_t* __restrict__ Zb, ...
;     ...
;         SLOAD(SE, ((j + 3 < NT) ? (j + 3) : (NT - 1)) * KVBLK); SBAR();
;         pv_d0(o, vb0 + (int)SHM_V, pa0, pa1, pa2, pa3); partialSM(pA0, pA1, negBC);
;         __syncthreads(); SWAIT(); SWRITE(1, SO);
;         __syncthreads();
	s_nop 15
	v_pk_add_f32 v[110:111], v[182:183], v[110:111]
	v_pk_add_f32 v[108:109], v[182:183], v[108:109]
	v_pk_add_f32 v[106:107], v[182:183], v[106:107]
	v_pk_add_f32 v[104:105], v[182:183], v[104:105]
	v_pk_add_f32 v[102:103], v[182:183], v[102:103]
	v_pk_add_f32 v[100:101], v[182:183], v[100:101]
	v_pk_add_f32 v[98:99], v[182:183], v[98:99]
	v_pk_add_f32 v[96:97], v[182:183], v[96:97]
	v_pk_add_f32 v[78:79], v[182:183], v[78:79]
	v_pk_add_f32 v[76:77], v[182:183], v[76:77]
	v_pk_add_f32 v[74:75], v[182:183], v[74:75]
	v_pk_add_f32 v[72:73], v[182:183], v[72:73]
	v_pk_add_f32 v[70:71], v[182:183], v[70:71]
	v_pk_add_f32 v[68:69], v[182:183], v[68:69]
	v_pk_add_f32 v[66:67], v[182:183], v[66:67]
	v_pk_add_f32 v[64:65], v[182:183], v[64:65]
.Lat2_noshift_B:
	s_waitcnt lgkmcnt(6)
	v_mfma_f32_32x32x16_bf16 v[0:15], v[160:163], v[236:239], v[0:15]
	ds_read_b64_tr_b16 v[236:237], v205 offset:512
	ds_read_b64_tr_b16 v[238:239], v205 offset:2560
	s_waitcnt lgkmcnt(6)
	v_mfma_f32_32x32x16_bf16 v[0:15], v[164:167], v[240:243], v[0:15]
	ds_read_b64_tr_b16 v[240:241], v205 offset:4608
	ds_read_b64_tr_b16 v[242:243], v205 offset:6656
	s_waitcnt vmcnt(0)
	ds_write_b128 v209, v[148:151] offset:49152
	v_exp_f32_e32 v233, v96
	v_exp_f32_e32 v235, v97
	s_waitcnt lgkmcnt(7)
	v_mfma_f32_32x32x16_bf16 v[0:15], v[168:171], v[244:247], v[0:15]
	ds_read_b64_tr_b16 v[244:245], v205 offset:8704
	ds_read_b64_tr_b16 v[246:247], v205 offset:10752
	ds_write_b128 v210, v[152:155] offset:49152
	v_exp_f32_e32 v231, v98
	v_exp_f32_e32 v234, v99
	s_waitcnt lgkmcnt(8)
	v_mfma_f32_32x32x16_bf16 v[0:15], v[172:175], v[248:251], v[0:15]
	ds_read_b64_tr_b16 v[248:249], v205 offset:12800
	ds_read_b64_tr_b16 v[250:251], v205 offset:14848
	ds_write_b128 v207, v[144:147] offset:0
	v_exp_f32_e32 v230, v100
	v_exp_f32_e32 v232, v101
	s_waitcnt lgkmcnt(9)
	v_mfma_f32_32x32x16_bf16 v[16:31], v[160:163], v[236:239], v[16:31]
	ds_read_b64_tr_b16 v[236:237], v205 offset:1024
	ds_read_b64_tr_b16 v[238:239], v205 offset:3072
	ds_write_b128 v208, v[156:159] offset:0
	v_exp_f32_e32 v228, v102
	v_exp_f32_e32 v229, v103
	s_waitcnt lgkmcnt(10)
	v_mfma_f32_32x32x16_bf16 v[16:31], v[164:167], v[240:243], v[16:31]
	ds_read_b64_tr_b16 v[240:241], v205 offset:5120
	ds_read_b64_tr_b16 v[242:243], v205 offset:7168
	v_exp_f32_e32 v225, v104
	v_exp_f32_e32 v227, v105
	s_waitcnt lgkmcnt(9)
	v_mfma_f32_32x32x16_bf16 v[16:31], v[168:171], v[244:247], v[16:31]
	ds_read_b64_tr_b16 v[244:245], v205 offset:9216
	ds_read_b64_tr_b16 v[246:247], v205 offset:11264
	v_lshl_add_u64 v[144:145], v[190:191], 0, s[98:99]
	global_load_dwordx4 v[156:159], v[190:191], off
	global_load_dwordx4 v[144:147], v[144:145], off
	v_exp_f32_e32 v224, v106
	v_exp_f32_e32 v226, v107
	s_waitcnt lgkmcnt(8)
	v_mfma_f32_32x32x16_bf16 v[16:31], v[172:175], v[248:251], v[16:31]
	ds_read_b64_tr_b16 v[248:249], v205 offset:13312
	ds_read_b64_tr_b16 v[250:251], v205 offset:15360
	v_exp_f32_e32 v221, v108
	v_exp_f32_e32 v223, v109
	s_waitcnt lgkmcnt(7)
	v_mfma_f32_32x32x16_bf16 v[32:47], v[160:163], v[236:239], v[32:47]
	ds_read_b64_tr_b16 v[236:237], v205 offset:1536
	ds_read_b64_tr_b16 v[238:239], v205 offset:3584
	v_lshl_add_u64 v[190:191], v[190:191], 0, s[100:101]
	v_lshl_add_u64 v[148:149], v[190:191], 0, s[98:99]
	global_load_dwordx4 v[152:155], v[190:191], off offset:-512
	global_load_dwordx4 v[148:151], v[148:149], off offset:-512
	v_exp_f32_e32 v181, v110
	v_exp_f32_e32 v222, v111
	s_waitcnt lgkmcnt(6)
	v_mfma_f32_32x32x16_bf16 v[32:47], v[164:167], v[240:243], v[32:47]
	ds_read_b64_tr_b16 v[240:241], v205 offset:5632
	ds_read_b64_tr_b16 v[242:243], v205 offset:7680
	v_exp_f32_e32 v64, v64
	v_exp_f32_e32 v65, v65
	s_waitcnt lgkmcnt(6)
	v_mfma_f32_32x32x16_bf16 v[32:47], v[168:171], v[244:247], v[32:47]
	ds_read_b64_tr_b16 v[244:245], v205 offset:9728
	ds_read_b64_tr_b16 v[246:247], v205 offset:11776
	v_exp_f32_e32 v66, v66
	v_exp_f32_e32 v67, v67
	s_waitcnt lgkmcnt(6)
	v_mfma_f32_32x32x16_bf16 v[32:47], v[172:175], v[248:251], v[32:47]
	ds_read_b64_tr_b16 v[248:249], v205 offset:13824
	ds_read_b64_tr_b16 v[250:251], v205 offset:15872
	v_exp_f32_e32 v68, v68
	v_exp_f32_e32 v69, v69
	s_waitcnt lgkmcnt(6)
	v_mfma_f32_32x32x16_bf16 v[48:63], v[160:163], v[236:239], v[48:63]
	v_exp_f32_e32 v70, v70
	v_exp_f32_e32 v71, v71
	s_waitcnt lgkmcnt(4)
	v_mfma_f32_32x32x16_bf16 v[48:63], v[164:167], v[240:243], v[48:63]
	v_exp_f32_e32 v72, v72
	v_exp_f32_e32 v73, v73
	v_exp_f32_e32 v74, v74
	s_waitcnt lgkmcnt(2)
	v_mfma_f32_32x32x16_bf16 v[48:63], v[168:171], v[244:247], v[48:63]
	v_exp_f32_e32 v75, v75
	v_exp_f32_e32 v76, v76
	v_exp_f32_e32 v77, v77
	s_waitcnt lgkmcnt(0)
	v_mfma_f32_32x32x16_bf16 v[48:63], v[172:175], v[248:251], v[48:63]
	v_exp_f32_e32 v78, v78
	v_exp_f32_e32 v79, v79
	s_waitcnt lgkmcnt(0)
	s_add_i32 s22, s39, 2
	s_cmp_ge_u32 s39, s33
	s_barrier
	s_cbranch_scc1 .Lat2_tail
	s_mov_b32 s39, s22
	s_branch .LBB0_490

; #define SBAR() __builtin_amdgcn_sched_barrier(0)
; template <int D0> __device__ __forceinline__ void pv_one(f32x16& od, int vb, bf16x8 pa0, bf16x8 pa1, bf16x8 pa2, bf16x8 pa3) {
;     const s16x4 l0 = tr_read<v_rd_off(D0, 0, 0)>(vb), h0 = tr_read<v_rd_off(D0, 0, 1)>(vb), l1 = tr_read<v_rd_off(D0, 1, 0)>(vb), h1 = tr_read<v_rd_off(D0, 1, 1)>(vb);
;     const s16x4 l2 = tr_read<v_rd_off(D0, 2, 0)>(vb), h2 = tr_read<v_rd_off(D0, 2, 1)>(vb), l3 = tr_read<v_rd_off(D0, 3, 0)>(vb), h3 = tr_read<v_rd_off(D0, 3, 1)>(vb);
;     asm volatile("s_waitcnt lgkmcnt(0)" ::: "memory"); SBAR();
;     ...
;     od = __builtin_amdgcn_mfma_f32_32x32x16_bf16(pa0, PK(l0, h0), od, 0, 0, 0);
;     od = __builtin_amdgcn_mfma_f32_32x32x16_bf16(pa1, PK(l1, h1), od, 0, 0, 0);
;     od = __builtin_amdgcn_mfma_f32_32x32x16_bf16(pa2, PK(l2, h2), od, 0, 0, 0);
;     od = __builtin_amdgcn_mfma_f32_32x32x16_bf16(pa3, PK(l3, h3), od, 0, 0, 0);
;     ...
; }
; __device__ __forceinline__ void pv_d0(f32x16* o, int vb, bf16x8 pa0, bf16x8 pa1, bf16x8 pa2, bf16x8 pa3) {
;     pv_one<0>(o[0], vb, pa0, pa1, pa2, pa3); pv_one<1>(o[1], vb, pa0, pa1, pa2, pa3); pv_one<2>(o[2], vb, pa0, pa1, pa2, pa3); pv_one<3>(o[3], vb, pa0, pa1, pa2, pa3);
; __device__ __forceinline__ void attn_body(const bf16_t* __restrict__ Qb, const bf16_t* __restrict__ Kh, const bf16_t* __restrict__ Vh, const bf16_t* __restrict__ Zb, ...
;     ...
;     SBAR(); qkt(pB0, pB1, (bf16_t*)((char*)K_lds + SHM_K), qr, r32, hi);
;     finishSM(pA0, pA1, 1.f, l_reg, pa0, pa1, pa2, pa3); SBAR();
;     pv_d0(o, vb0, pa0, pa1, pa2, pa3); partialSM(pB0, pB1, negBC);
;     __syncthreads();
.Lat2_noshift_TA:
	s_waitcnt lgkmcnt(6)
	v_mfma_f32_32x32x16_bf16 v[0:15], v[160:163], v[236:239], v[0:15]
	ds_read_b64_tr_b16 v[236:237], v206 offset:512
	ds_read_b64_tr_b16 v[238:239], v206 offset:2560
	s_waitcnt lgkmcnt(6)
	v_mfma_f32_32x32x16_bf16 v[0:15], v[164:167], v[240:243], v[0:15]
	ds_read_b64_tr_b16 v[240:241], v206 offset:4608
	ds_read_b64_tr_b16 v[242:243], v206 offset:6656
	s_waitcnt vmcnt(0)
	ds_write_b128 v207, v[144:147] offset:16384
	v_exp_f32_e32 v181, v96
	v_exp_f32_e32 v221, v97
	s_waitcnt lgkmcnt(7)
	v_mfma_f32_32x32x16_bf16 v[0:15], v[168:171], v[244:247], v[0:15]
	ds_read_b64_tr_b16 v[244:245], v206 offset:8704
	ds_read_b64_tr_b16 v[246:247], v206 offset:10752
	ds_write_b128 v208, v[156:159] offset:16384
	v_exp_f32_e32 v222, v98
	v_exp_f32_e32 v223, v99
	s_waitcnt lgkmcnt(8)
	v_mfma_f32_32x32x16_bf16 v[0:15], v[172:175], v[248:251], v[0:15]
	ds_read_b64_tr_b16 v[248:249], v206 offset:12800
	ds_read_b64_tr_b16 v[250:251], v206 offset:14848
	v_exp_f32_e32 v224, v100
	v_exp_f32_e32 v225, v101
	s_waitcnt lgkmcnt(8)
	v_mfma_f32_32x32x16_bf16 v[16:31], v[160:163], v[236:239], v[16:31]
	ds_read_b64_tr_b16 v[236:237], v206 offset:1024
	ds_read_b64_tr_b16 v[238:239], v206 offset:3072
	v_exp_f32_e32 v226, v102
	v_exp_f32_e32 v227, v103
	s_waitcnt lgkmcnt(8)
	v_mfma_f32_32x32x16_bf16 v[16:31], v[164:167], v[240:243], v[16:31]
	ds_read_b64_tr_b16 v[240:241], v206 offset:5120
	ds_read_b64_tr_b16 v[242:243], v206 offset:7168
	v_exp_f32_e32 v228, v104
	v_exp_f32_e32 v229, v105
	s_waitcnt lgkmcnt(7)
	v_mfma_f32_32x32x16_bf16 v[16:31], v[168:171], v[244:247], v[16:31]
	ds_read_b64_tr_b16 v[244:245], v206 offset:9216
	ds_read_b64_tr_b16 v[246:247], v206 offset:11264
	v_exp_f32_e32 v230, v106
	v_exp_f32_e32 v231, v107
	s_waitcnt lgkmcnt(6)
	v_mfma_f32_32x32x16_bf16 v[16:31], v[172:175], v[248:251], v[16:31]
	ds_read_b64_tr_b16 v[248:249], v206 offset:13312
	ds_read_b64_tr_b16 v[250:251], v206 offset:15360
	v_exp_f32_e32 v232, v108
	v_exp_f32_e32 v233, v109
	s_waitcnt lgkmcnt(6)
	v_mfma_f32_32x32x16_bf16 v[32:47], v[160:163], v[236:239], v[32:47]
	ds_read_b64_tr_b16 v[236:237], v206 offset:1536
	ds_read_b64_tr_b16 v[238:239], v206 offset:3584
	v_exp_f32_e32 v234, v110
	v_exp_f32_e32 v235, v111
	s_waitcnt lgkmcnt(6)
	v_mfma_f32_32x32x16_bf16 v[32:47], v[164:167], v[240:243], v[32:47]
	ds_read_b64_tr_b16 v[240:241], v206 offset:5632
	ds_read_b64_tr_b16 v[242:243], v206 offset:7680
	v_exp_f32_e32 v80, v80
	v_exp_f32_e32 v81, v81
	s_waitcnt lgkmcnt(6)
	v_mfma_f32_32x32x16_bf16 v[32:47], v[168:171], v[244:247], v[32:47]
	ds_read_b64_tr_b16 v[244:245], v206 offset:9728
	ds_read_b64_tr_b16 v[246:247], v206 offset:11776
	v_exp_f32_e32 v82, v82
	v_exp_f32_e32 v83, v83
	s_waitcnt lgkmcnt(6)
	v_mfma_f32_32x32x16_bf16 v[32:47], v[172:175], v[248:251], v[32:47]
	ds_read_b64_tr_b16 v[248:249], v206 offset:13824
	ds_read_b64_tr_b16 v[250:251], v206 offset:15872
	v_exp_f32_e32 v84, v84
	v_exp_f32_e32 v85, v85
	s_waitcnt lgkmcnt(6)
	v_mfma_f32_32x32x16_bf16 v[48:63], v[160:163], v[236:239], v[48:63]
	v_exp_f32_e32 v86, v86
	v_exp_f32_e32 v87, v87
	s_waitcnt lgkmcnt(4)
	v_mfma_f32_32x32x16_bf16 v[48:63], v[164:167], v[240:243], v[48:63]
	v_exp_f32_e32 v88, v88
	v_exp_f32_e32 v89, v89
	v_exp_f32_e32 v90, v90
	s_waitcnt lgkmcnt(2)
	v_mfma_f32_32x32x16_bf16 v[48:63], v[168:171], v[244:247], v[48:63]
	v_exp_f32_e32 v91, v91
	v_exp_f32_e32 v92, v92
	v_exp_f32_e32 v93, v93
	s_waitcnt lgkmcnt(0)
	v_mfma_f32_32x32x16_bf16 v[48:63], v[172:175], v[248:251], v[48:63]
	v_exp_f32_e32 v94, v94
	v_exp_f32_e32 v95, v95
	s_waitcnt lgkmcnt(0)
	s_barrier
; #define SBAR() __builtin_amdgcn_sched_barrier(0)
; __device__ __forceinline__ void finishSM(f32x16& p0, f32x16& p1, float alpha, float& l_reg, bf16x8& pa0, bf16x8& pa1, bf16x8& pa2, bf16x8& pa3) {
;     for (int r = 0; r < 16; ++r) p1[r] = __builtin_amdgcn_exp2f(p1[r]);
;     float ps = 0; for (int r = 0; r < 16; ++r) ps += p0[r]; for (int r = 0; r < 16; ++r) ps += p1[r];
;     { auto rr = __builtin_amdgcn_permlane32_swap(__float_as_uint(ps), __float_as_uint(ps), false, false);
;       ps = __uint_as_float(rr[0]) + __uint_as_float(rr[1]); }
;     l_reg = l_reg * alpha + ps;
;     ...
;     PK4(p0, 0, pa0); PK4(p0, 8, pa1); PK4(p1, 0, pa2); PK4(p1, 8, pa3);
;     ...
; }
; __device__ __forceinline__ void attn_body(const bf16_t* __restrict__ Qb, const bf16_t* __restrict__ Kh, const bf16_t* __restrict__ Vh, const bf16_t* __restrict__ Zb, ...
;     ...
;     finishSM(pB0, pB1, 1.f, l_reg, pa0, pa1, pa2, pa3); SBAR();
;     pv_d0(o, vb0 + (int)SHM_V, pa0, pa1, pa2, pa3);
;     __builtin_amdgcn_s_setprio(0);
;     if (hi == 0) li_l[r32] = l_reg; asm volatile("s_waitcnt lgkmcnt(0)" ::: "memory");
	ds_read_b64_tr_b16 v[236:237], v205 offset:0
	ds_read_b64_tr_b16 v[238:239], v205 offset:2048
	ds_read_b64_tr_b16 v[240:241], v205 offset:4096
	ds_read_b64_tr_b16 v[242:243], v205 offset:6144
	ds_read_b64_tr_b16 v[244:245], v205 offset:8192
	ds_read_b64_tr_b16 v[246:247], v205 offset:10240
	ds_read_b64_tr_b16 v[248:249], v205 offset:12288
	ds_read_b64_tr_b16 v[250:251], v205 offset:14336
	v_add_f32_e32 v219, v181, v221
	v_cvt_pk_bf16_f32 v160, v181, v221
	v_add_f32_e32 v219, v222, v219
	v_cvt_pk_bf16_f32 v161, v222, v223
	v_add_f32_e32 v219, v223, v219
	v_cvt_pk_bf16_f32 v162, v224, v225
	v_add_f32_e32 v219, v224, v219
	v_cvt_pk_bf16_f32 v163, v226, v227
	v_add_f32_e32 v219, v225, v219
	v_cvt_pk_bf16_f32 v164, v228, v229
	v_add_f32_e32 v219, v226, v219
	v_cvt_pk_bf16_f32 v165, v230, v231
	v_add_f32_e32 v219, v227, v219
	v_cvt_pk_bf16_f32 v166, v232, v233
	v_add_f32_e32 v219, v228, v219
	v_cvt_pk_bf16_f32 v167, v234, v235
	v_add_f32_e32 v219, v229, v219
	v_cvt_pk_bf16_f32 v168, v80, v81
	v_add_f32_e32 v219, v230, v219
	v_cvt_pk_bf16_f32 v169, v82, v83
	v_add_f32_e32 v219, v231, v219
	v_cvt_pk_bf16_f32 v170, v84, v85
	v_add_f32_e32 v219, v232, v219
	v_cvt_pk_bf16_f32 v171, v86, v87
	v_add_f32_e32 v219, v233, v219
	v_cvt_pk_bf16_f32 v172, v88, v89
	v_add_f32_e32 v219, v234, v219
	v_cvt_pk_bf16_f32 v173, v90, v91
	v_add_f32_e32 v219, v235, v219
	v_cvt_pk_bf16_f32 v174, v92, v93
	v_add_f32_e32 v219, v80, v219
	v_cvt_pk_bf16_f32 v175, v94, v95
	v_add_f32_e32 v219, v81, v219
	v_permlane32_swap_b32_e32 v160, v162
	v_add_f32_e32 v219, v82, v219
	v_permlane32_swap_b32_e32 v161, v163
	v_add_f32_e32 v219, v83, v219
	v_permlane32_swap_b32_e32 v164, v166
	v_add_f32_e32 v219, v84, v219
	v_permlane32_swap_b32_e32 v165, v167
	v_add_f32_e32 v219, v85, v219
	v_permlane32_swap_b32_e32 v168, v170
	v_add_f32_e32 v219, v86, v219
	v_permlane32_swap_b32_e32 v169, v171
	v_add_f32_e32 v219, v87, v219
	v_permlane32_swap_b32_e32 v172, v174
	v_add_f32_e32 v219, v88, v219
	v_permlane32_swap_b32_e32 v173, v175
	v_add_f32_e32 v219, v89, v219
	v_add_f32_e32 v219, v90, v219
	v_add_f32_e32 v219, v91, v219
	v_add_f32_e32 v219, v92, v219
	v_add_f32_e32 v219, v93, v219
	v_add_f32_e32 v219, v94, v219
	v_add_f32_e32 v219, v95, v219
	v_mov_b32_e32 v220, v219
	s_nop 1
	v_permlane32_swap_b32_e32 v219, v220
	v_add_f32_e32 v219, v219, v220
	v_add_f32_e32 v204, v204, v219
	s_waitcnt lgkmcnt(6)
	v_mfma_f32_32x32x16_bf16 v[0:15], v[160:163], v[236:239], v[0:15]
	ds_read_b64_tr_b16 v[236:237], v205 offset:512
	ds_read_b64_tr_b16 v[238:239], v205 offset:2560
	s_waitcnt lgkmcnt(6)
	v_mfma_f32_32x32x16_bf16 v[0:15], v[164:167], v[240:243], v[0:15]
	ds_read_b64_tr_b16 v[240:241], v205 offset:4608
	ds_read_b64_tr_b16 v[242:243], v205 offset:6656
	s_waitcnt lgkmcnt(6)
	v_mfma_f32_32x32x16_bf16 v[0:15], v[168:171], v[244:247], v[0:15]
	ds_read_b64_tr_b16 v[244:245], v205 offset:8704
	ds_read_b64_tr_b16 v[246:247], v205 offset:10752
	s_waitcnt lgkmcnt(6)
	v_mfma_f32_32x32x16_bf16 v[0:15], v[172:175], v[248:251], v[0:15]
	ds_read_b64_tr_b16 v[248:249], v205 offset:12800
	ds_read_b64_tr_b16 v[250:251], v205 offset:14848
	s_waitcnt lgkmcnt(6)
	v_mfma_f32_32x32x16_bf16 v[16:31], v[160:163], v[236:239], v[16:31]
	ds_read_b64_tr_b16 v[236:237], v205 offset:1024
	ds_read_b64_tr_b16 v[238:239], v205 offset:3072
	s_waitcnt lgkmcnt(6)
	v_mfma_f32_32x32x16_bf16 v[16:31], v[164:167], v[240:243], v[16:31]
	ds_read_b64_tr_b16 v[240:241], v205 offset:5120
	ds_read_b64_tr_b16 v[242:243], v205 offset:7168
	s_waitcnt lgkmcnt(6)
	v_mfma_f32_32x32x16_bf16 v[16:31], v[168:171], v[244:247], v[16:31]
	ds_read_b64_tr_b16 v[244:245], v205 offset:9216
	ds_read_b64_tr_b16 v[246:247], v205 offset:11264
	s_waitcnt lgkmcnt(6)
	v_mfma_f32_32x32x16_bf16 v[16:31], v[172:175], v[248:251], v[16:31]
	ds_read_b64_tr_b16 v[248:249], v205 offset:13312
	ds_read_b64_tr_b16 v[250:251], v205 offset:15360
	s_waitcnt lgkmcnt(6)
	v_mfma_f32_32x32x16_bf16 v[32:47], v[160:163], v[236:239], v[32:47]
	ds_read_b64_tr_b16 v[236:237], v205 offset:1536
	ds_read_b64_tr_b16 v[238:239], v205 offset:3584
	s_waitcnt lgkmcnt(6)
	v_mfma_f32_32x32x16_bf16 v[32:47], v[164:167], v[240:243], v[32:47]
	ds_read_b64_tr_b16 v[240:241], v205 offset:5632
	ds_read_b64_tr_b16 v[242:243], v205 offset:7680
	s_waitcnt lgkmcnt(6)
	v_mfma_f32_32x32x16_bf16 v[32:47], v[168:171], v[244:247], v[32:47]
	ds_read_b64_tr_b16 v[244:245], v205 offset:9728
	ds_read_b64_tr_b16 v[246:247], v205 offset:11776
	s_waitcnt lgkmcnt(6)
	v_mfma_f32_32x32x16_bf16 v[32:47], v[172:175], v[248:251], v[32:47]
	ds_read_b64_tr_b16 v[248:249], v205 offset:13824
	ds_read_b64_tr_b16 v[250:251], v205 offset:15872
	s_waitcnt lgkmcnt(6)
	v_mfma_f32_32x32x16_bf16 v[48:63], v[160:163], v[236:239], v[48:63]
	s_waitcnt lgkmcnt(4)
	v_mfma_f32_32x32x16_bf16 v[48:63], v[164:167], v[240:243], v[48:63]
	s_waitcnt lgkmcnt(2)
	v_mfma_f32_32x32x16_bf16 v[48:63], v[168:171], v[244:247], v[48:63]
	s_waitcnt lgkmcnt(0)
	v_mfma_f32_32x32x16_bf16 v[48:63], v[172:175], v[248:251], v[48:63]
	v_mov_b32_e32 v64, 0
	v_mov_b32_e32 v65, 0
	v_mov_b32_e32 v67, 0
	v_mov_b32_e32 v68, 0
	v_and_b32_e32 v66, 0x3fffffc0, v200
	v_lshl_add_u32 v66, v66, 2, s36
	s_setprio 0
	v_cmp_gt_u32_e32 vcc, 32, v203
	s_and_saveexec_b64 s[6:7], vcc
	s_cbranch_execz .LBB0_480
	v_add_f32_e32 v64, v64, v65
	v_add_f32_e32 v64, v204, v64
	v_add_f32_e32 v67, v67, v68
	v_lshl_add_u32 v65, v201, 2, v66
	v_add_f32_e32 v64, v64, v67
	ds_write_b32 v65, v64
	s_branch .LBB0_480

; __global__ __launch_bounds__(512, 2) void mk_fwd(Params p) {
;     extern __shared__ __attribute__((aligned(16))) unsigned char smem[];
	.amdhsa_kernel _Z6mk_fwd6Params
		.amdhsa_group_segment_fixed_size 0
		.amdhsa_private_segment_fixed_size 0
		.amdhsa_kernarg_size 440
		.amdhsa_user_sgpr_count 2
		.amdhsa_user_sgpr_dispatch_ptr 0
		.amdhsa_user_sgpr_queue_ptr 0
		.amdhsa_user_sgpr_kernarg_segment_ptr 1
		.amdhsa_user_sgpr_dispatch_id 0
		.amdhsa_user_sgpr_kernarg_preload_length 0
		.amdhsa_user_sgpr_kernarg_preload_offset 0
		.amdhsa_user_sgpr_private_segment_size 0
		.amdhsa_uses_dynamic_stack 0
		.amdhsa_enable_private_segment 0
		.amdhsa_system_sgpr_workgroup_id_x 1
		.amdhsa_system_sgpr_workgroup_id_y 0
		.amdhsa_system_sgpr_workgroup_id_z 0
		.amdhsa_system_sgpr_workgroup_info 0
		.amdhsa_system_vgpr_workitem_id 2
		.amdhsa_next_free_vgpr 255
		.amdhsa_next_free_sgpr 102
		.amdhsa_accum_offset 256
		.amdhsa_reserve_vcc 1
		.amdhsa_float_round_mode_32 0
		.amdhsa_float_round_mode_16_64 0
		.amdhsa_float_denorm_mode_32 3
		.amdhsa_float_denorm_mode_16_64 3
		.amdhsa_dx10_clamp 1
		.amdhsa_ieee_mode 1
		.amdhsa_fp16_overflow 0
		.amdhsa_tg_split 0
		.amdhsa_exception_fp_ieee_invalid_op 0
		.amdhsa_exception_fp_denorm_src 0
		.amdhsa_exception_fp_ieee_div_zero 0
		.amdhsa_exception_fp_ieee_overflow 0
		.amdhsa_exception_fp_ieee_underflow 0
		.amdhsa_exception_fp_ieee_inexact 0
		.amdhsa_exception_int_div_zero 0
	.end_amdhsa_kernel

; __global__ __launch_bounds__(512, 2) void mk_fwd(Params p) {
;     extern __shared__ __attribute__((aligned(16))) unsigned char smem[];
amdhsa.kernels:
  - .agpr_count:     0
    .args:
      - .offset:         0
        .size:           184
        .value_kind:     by_value
      - .offset:         184
        .size:           4
        .value_kind:     hidden_block_count_x
      - .offset:         188
        .size:           4
        .value_kind:     hidden_block_count_y
      - .offset:         192
        .size:           4
        .value_kind:     hidden_block_count_z
      - .offset:         196
        .size:           2
        .value_kind:     hidden_group_size_x
      - .offset:         198
        .size:           2
        .value_kind:     hidden_group_size_y
      - .offset:         200
        .size:           2
        .value_kind:     hidden_group_size_z
      - .offset:         202
        .size:           2
        .value_kind:     hidden_remainder_x
      - .offset:         204
        .size:           2
        .value_kind:     hidden_remainder_y
      - .offset:         206
        .size:           2
        .value_kind:     hidden_remainder_z
      - .offset:         224
        .size:           8
        .value_kind:     hidden_global_offset_x
      - .offset:         232
        .size:           8
        .value_kind:     hidden_global_offset_y
      - .offset:         240
        .size:           8
        .value_kind:     hidden_global_offset_z
      - .offset:         248
        .size:           2
        .value_kind:     hidden_grid_dims
      - .offset:         272
        .size:           8
        .value_kind:     hidden_multigrid_sync_arg
      - .offset:         304
        .size:           4
        .value_kind:     hidden_dynamic_lds_size
    .group_segment_fixed_size: 0
    .kernarg_segment_align: 8
    .kernarg_segment_size: 440
    .language:       OpenCL C
    .language_version:
      - 2
      - 0
    .max_flat_workgroup_size: 512
    .name:           _Z6mk_fwd6Params
    .private_segment_fixed_size: 0
    .sgpr_count:     108
    .sgpr_spill_count: 64
    .symbol:         _Z6mk_fwd6Params.kd
    .uniform_work_group_size: 1
    .uses_dynamic_stack: false
    .vgpr_count:     255
    .vgpr_spill_count: 0
    .wavefront_size: 64
